# pipelined global-attention loop with MFMA-first head, no static priority raise (same code size as the previous version)
# baseline (speedup 1.0000x reference)
; #define LAS __attribute__((address_space(3)))
; __device__ __forceinline__ unsigned pk2(float lo, float hi) { f32x2_t v = {lo, hi}; bf16x2_t b = __builtin_convertvector(v, bf16x2_t); return __builtin_bit_cast(unsigned, b); }
; template <bool TRACK> ...
;     ...
;     { const int qrow = wave * 32 + r32; const bf16* qp = Qraw + (size_t)qrow * INW + hi * 8;
;       float qv[4][8]; float ss = 0.f;
; #pragma unroll
;       for (int d = 0; d < 4; ++d) { unpack8(*(const u32x4*)(qp + d * 16), qv[d]);
; #pragma unroll
;           for (int e = 0; e < 8; ++e) ss += qv[d][e] * qv[d][e]; }
;       ss += __shfl_xor(ss, 32);
;       const float rs = rsqrtf(ss * (1.0f / 64.0f) + 1e-6f) * (0.125f * LOG2E);
; #pragma unroll
;       for (int d = 0; d < 4; ++d) { const f32x4 w0 = *(const f32x4*)(qnw + d * 16 + hi * 8), w1 = *(const f32x4*)(qnw + d * 16 + hi * 8 + 4);
;           qv[d][0] *= rs * w0.x; qv[d][1] *= rs * w0.y; qv[d][2] *= rs * w0.z; qv[d][3] *= rs * w0.w; qv[d][4] *= rs * w1.x; qv[d][5] *= rs * w1.y; qv[d][6] *= rs * w1.z; qv[d][7] *= rs * w1.w; }
;       if (tpos0 >= 0) { const float* cp = ropet + (size_t)(tpos0 + qrow) * 32 + hi * 8; const float* sp = cp + 2048 * 32;
; #pragma unroll
;           for (int ax = 0; ax < 2; ++ax) { const f32x4 c0 = *(const f32x4*)(cp + ax * 16), c1 = *(const f32x4*)(cp + ax * 16 + 4), s0_ = *(const f32x4*)(sp + ax * 16), s1_ = *(const f32x4*)(sp + ax * 16 + 4);
;               const float cc[8] = {c0.x, c0.y, c0.z, c0.w, c1.x, c1.y, c1.z, c1.w}, sn[8] = {s0_.x, s0_.y, s0_.z, s0_.w, s1_.x, s1_.y, s1_.z, s1_.w};
; #pragma unroll
;               for (int e = 0; e < 8; ++e) { const float xa = qv[2 * ax][e], xb = qv[2 * ax + 1][e]; qv[2 * ax][e] = xa * cc[e] - xb * sn[e]; qv[2 * ax + 1][e] = xb * cc[e] + xa * sn[e]; } } }
; #pragma unroll
;       for (int d = 0; d < 4; ++d) { u32x4 w; w.x = pk2(qv[d][0], qv[d][1]); w.y = pk2(qv[d][2], qv[d][3]); w.z = pk2(qv[d][4], qv[d][5]); w.w = pk2(qv[d][6], qv[d][7]); qf[d] = __builtin_bit_cast(bf16x8, w); } }
;     __syncthreads();
;     *(LAS u32x4*)(lds + (srow * 72 + sc * 8) * 2) = kreg; { LAS u32x2* vw_ = (LAS u32x2*)(lds + 9216 + (srow * 68 + sc * 8) * 2); vw_[0] = (u32x2){vreg.x, vreg.y}; vw_[1] = (u32x2){vreg.z, vreg.w}; }
;     __syncthreads();
.LBB0_165:
	s_andn2_saveexec_b64 s[48:49], s[48:49]
	s_cbranch_execz .LBB0_169
	ds_bpermute_b32 v19, v188, v18
	s_mov_b32 s4, 0x800000
	s_add_i32 s51, s51, s73
	s_and_b32 s20, s51, 0x1fff
	s_mul_i32 s22, s20, 0x48000
	s_waitcnt lgkmcnt(0)
	v_add_f32_e32 v18, v18, v19
	v_fmamk_f32 v18, v18, 0x3c800000, v163
	v_cmp_gt_f32_e32 vcc, s4, v18
	v_mul_f32_e32 v19, 0x4b800000, v18
	s_add_u32 s20, s50, s22
	v_cndmask_b32_e32 v18, v18, v19, vcc
	v_rsq_f32_e32 v18, v18
	s_addc_u32 s21, 0, 0
	v_mov_b32_e32 v135, v1
	v_readlane_b32 s4, v250, 63
	v_mul_f32_e32 v19, 0x45800000, v18
	v_cndmask_b32_e32 v18, v18, v19, vcc
	v_mul_f32_e32 v70, 0x3e38aa3b, v18
	global_load_dwordx4 v[26:29], v[16:17], off offset:192
	global_load_dwordx4 v[18:21], v[16:17], off offset:144
	global_load_dwordx4 v[30:33], v[16:17], off offset:128
	global_load_dwordx4 v[72:75], v[16:17], off offset:16
	global_load_dwordx4 v[76:79], v[16:17], off
	global_load_dwordx4 v[80:83], v[16:17], off offset:80
	global_load_dwordx4 v[84:87], v[16:17], off offset:64
	global_load_dwordx4 v[88:91], v[22:23], off offset:16
	global_load_dwordx4 v[92:95], v[22:23], off
	global_load_dwordx4 v[96:99], v[14:15], off offset:16
	s_nop 0
	global_load_dwordx4 v[14:17], v[14:15], off
	s_waitcnt vmcnt(11)
	v_pk_mul_f32 v[10:11], v[10:11], v[70:71] op_sel_hi:[1,0]
	v_pk_mul_f32 v[12:13], v[12:13], v[70:71] op_sel_hi:[1,0]
	v_pk_mul_f32 v[40:41], v[10:11], v[40:41]
	v_pk_mul_f32 v[12:13], v[12:13], v[36:37]
	v_readlane_b32 s5, v249, 0
	s_waitcnt vmcnt(10)
	v_pk_mul_f32 v[26:27], v[26:27], v[70:71] op_sel_hi:[1,0]
	s_waitcnt vmcnt(9)
	v_pk_mul_f32 v[10:11], v[18:19], v[70:71] op_sel_hi:[1,0]
	v_pk_mul_f32 v[28:29], v[28:29], v[70:71] op_sel_hi:[1,0]
	v_pk_mul_f32 v[18:19], v[10:11], v[38:39]
	s_waitcnt vmcnt(6)
	v_pk_mul_f32 v[68:69], v[76:77], v[70:71] op_sel_hi:[1,0]
	s_nop 0
	v_pk_mul_f32 v[66:67], v[68:69], v[66:67]
	s_waitcnt vmcnt(4)
	v_pk_mul_f32 v[68:69], v[84:85], v[70:71] op_sel_hi:[1,0]
	s_nop 0
	v_pk_mul_f32 v[68:69], v[68:69], v[64:65]
	s_waitcnt vmcnt(0)
	v_pk_mul_f32 v[64:65], v[14:15], v[68:69]
	v_pk_mul_f32 v[14:15], v[14:15], v[66:67]
	v_pk_fma_f32 v[64:65], v[92:93], v[66:67], v[64:65] neg_lo:[0,0,1] neg_hi:[0,0,1]
	v_pk_fma_f32 v[66:67], v[92:93], v[68:69], v[14:15]
	v_pk_mul_f32 v[14:15], v[78:79], v[70:71] op_sel_hi:[1,0]
	s_nop 0
	v_pk_mul_f32 v[14:15], v[14:15], v[62:63]
	v_pk_mul_f32 v[62:63], v[86:87], v[70:71] op_sel_hi:[1,0]
	s_nop 0
	v_pk_mul_f32 v[62:63], v[62:63], v[60:61]
	s_nop 0
	v_pk_mul_f32 v[60:61], v[16:17], v[62:63]
	s_nop 0
	v_pk_fma_f32 v[60:61], v[94:95], v[14:15], v[60:61] neg_lo:[0,0,1] neg_hi:[0,0,1]
	v_pk_mul_f32 v[14:15], v[16:17], v[14:15]
	v_pk_mul_f32 v[16:17], v[80:81], v[70:71] op_sel_hi:[1,0]
	v_pk_fma_f32 v[62:63], v[94:95], v[62:63], v[14:15]
	v_pk_mul_f32 v[14:15], v[72:73], v[70:71] op_sel_hi:[1,0]
	v_pk_mul_f32 v[16:17], v[16:17], v[56:57]
	v_pk_mul_f32 v[14:15], v[14:15], v[58:59]
	v_pk_mul_f32 v[56:57], v[96:97], v[16:17]
	v_cvt_pk_bf16_f32 v94, v64, v65
	v_pk_fma_f32 v[56:57], v[88:89], v[14:15], v[56:57] neg_lo:[0,0,1] neg_hi:[0,0,1]
	v_pk_mul_f32 v[14:15], v[96:97], v[14:15]
	v_cvt_pk_bf16_f32 v95, v60, v61
	v_pk_fma_f32 v[58:59], v[88:89], v[16:17], v[14:15]
	v_pk_mul_f32 v[16:17], v[82:83], v[70:71] op_sel_hi:[1,0]
	v_pk_mul_f32 v[14:15], v[74:75], v[70:71] op_sel_hi:[1,0]
	v_pk_mul_f32 v[16:17], v[16:17], v[24:25]
	v_pk_mul_f32 v[14:15], v[14:15], v[54:55]
	v_pk_mul_f32 v[24:25], v[98:99], v[16:17]
	v_cvt_pk_bf16_f32 v92, v58, v59
	v_pk_fma_f32 v[54:55], v[90:91], v[14:15], v[24:25] neg_lo:[0,0,1] neg_hi:[0,0,1]
	v_pk_mul_f32 v[14:15], v[98:99], v[14:15]
	v_cvt_pk_bf16_f32 v96, v56, v57
	v_pk_fma_f32 v[68:69], v[90:91], v[16:17], v[14:15]
	global_load_dwordx4 v[14:17], v[22:23], off offset:80
	global_load_dwordx4 v[72:75], v[22:23], off offset:64
	s_nop 0
	global_load_dwordx4 v[22:25], v[42:43], off offset:16
	global_load_dwordx4 v[76:79], v[42:43], off
	v_pk_mul_f32 v[42:43], v[26:27], v[52:53]
	v_pk_mul_f32 v[26:27], v[30:31], v[70:71] op_sel_hi:[1,0]
	s_nop 0
	v_pk_mul_f32 v[30:31], v[26:27], v[50:51]
	s_barrier
	ds_write_b128 v45, v[2:5]
	ds_write2_b64 v71, v[6:7], v[8:9] offset1:1
	v_mov_b32_e32 v45, v1
	v_lshl_add_u64 v[2:3], s[20:21], 0, v[44:45]
	s_add_u32 s20, s45, s22
	v_lshl_add_u64 v[2:3], v[2:3], 0, v[134:135]
	s_addc_u32 s21, 0, 0
	v_lshl_add_u64 v[114:115], s[4:5], 0, v[2:3]
	v_lshl_add_u64 v[2:3], s[20:21], 0, v[134:135]
	v_readlane_b32 s4, v249, 1
	v_lshl_add_u64 v[2:3], v[2:3], 0, v[0:1]
	v_readlane_b32 s5, v249, 2
	s_waitcnt lgkmcnt(0)
	s_barrier
; template <bool TRACK> ...
;     ...
;               for (int e = 0; e < 8; ++e) { const float xa = qv[2 * ax][e], xb = qv[2 * ax + 1][e]; qv[2 * ax][e] = xa * cc[e] - xb * sn[e]; qv[2 * ax + 1][e] = xb * cc[e] + xa * sn[e]; } } }
; #pragma unroll
;       for (int d = 0; d < 4; ++d) { u32x4 w; w.x = pk2(qv[d][0], qv[d][1]); w.y = pk2(qv[d][2], qv[d][3]); w.z = pk2(qv[d][4], qv[d][5]); w.w = pk2(qv[d][6], qv[d][7]); qf[d] = __builtin_bit_cast(bf16x8, w); } }
;     __syncthreads();
;     *(LAS u32x4*)(lds + (srow * 72 + sc * 8) * 2) = kreg; { LAS u32x2* vw_ = (LAS u32x2*)(lds + 9216 + (srow * 68 + sc * 8) * 2); vw_[0] = (u32x2){vreg.x, vreg.y}; vw_[1] = (u32x2){vreg.z, vreg.w}; }
;     __syncthreads();
;     f32x16 o0, o1;
; #pragma unroll
;     for (int r = 0; r < 16; ++r) { o0[r] = 0.f; o1[r] = 0.f; }
;     float m = m_init, lsum = hi == 0 ? l_init : 0.f;
;     f32x16 negm, lacc;
; #pragma unroll
;     for (int r = 0; r < 16; ++r) { negm[r] = TRACK ? -m_init : 0.f; lacc[r] = TRACK ? 0.f : l_init * __builtin_amdgcn_exp2f(m_init); }
;     const bf16x8 ones = __builtin_bit_cast(bf16x8, ((u32x4){0x3f803f80u, 0x3f803f80u, 0x3f803f80u, 0x3f803f80u}));
;     for (int j = 0; j < nt; ++j) {
;         const int cur = j & 1; const int tl = j < n0 ? j : t1lo + (j - n0);
;         if (j + 1 < nt) { const int tn = (j + 1) < n0 ? (j + 1) : t1lo + (j + 1 - n0);
;             kreg = *(const u32x4*)(Kb + (size_t)(tn * 64 + srow) * 64 + sc * 8); vreg = *(const u32x4*)(Vtb + (size_t)srow * KEYS + tn * 64 + sc * 8); }
;         bool active = true; bool mt = masked && j >= n0; const int kpos0 = (tl - 4) * 64;
;         if (mt) { const int qs = qstart + wave * 32; active = !(kpos0 > qs + 31 + 128 || kpos0 + 63 < qs - 128);
;             if (kpos0 >= qs + 31 - 128 && kpos0 + 63 <= qs + 128) mt = false; }
;         if (active) {
;             const LAS unsigned char* Kbuf = lds + cur * 18432; const LAS unsigned char* Vbuf = Kbuf + 9216;
;             f32x16 s0 = negm, s1 = negm;
;             u32x2 vq[8];
;             if constexpr (!TRACK) {
;             bf16x8 kf[8];
; #pragma unroll
;             for (int d = 0; d < 4; ++d) { kf[2 * d] = *(const LAS bf16x8*)(Kbuf + (r32 * 72 + d * 16 + hi * 8) * 2); kf[2 * d + 1] = *(const LAS bf16x8*)(Kbuf + ((32 + r32) * 72 + d * 16 + hi * 8) * 2); }
;             __builtin_amdgcn_sched_barrier(0);
; #pragma unroll
	v_lshl_add_u64 v[116:117], s[4:5], 0, v[2:3]
	global_load_dwordx4 v[230:233], v[114:115], off
	v_mov_b32_e32 v2, 0
	v_cvt_pk_bf16_f32 v90, v66, v67
	v_cvt_pk_bf16_f32 v91, v62, v63
	v_cvt_pk_bf16_f32 v93, v68, v69
	v_cvt_pk_bf16_f32 v97, v54, v55
	s_mov_b32 s20, 0
	v_mov_b32_e32 v3, v2
	v_mov_b32_e32 v4, v2
	v_mov_b32_e32 v5, v2
	v_mov_b32_e32 v6, v2
	v_mov_b32_e32 v7, v2
	v_mov_b32_e32 v8, v2
	v_mov_b32_e32 v9, v2
	v_mov_b32_e32 v36, v2
	v_mov_b32_e32 v37, v2
	v_mov_b32_e32 v38, v2
	v_mov_b32_e32 v39, v2
	v_mov_b32_e32 v44, v2
	v_mov_b32_e32 v45, v2
	s_mov_b64 s[4:5], 0x2000
	s_waitcnt vmcnt(2)
	v_pk_mul_f32 v[10:11], v[40:41], v[22:23]
	s_waitcnt vmcnt(1)
	v_pk_mul_f32 v[26:27], v[42:43], v[76:77]
	v_pk_fma_f32 v[10:11], v[18:19], v[14:15], v[10:11] neg_lo:[0,0,1] neg_hi:[0,0,1]
	v_pk_fma_f32 v[26:27], v[30:31], v[72:73], v[26:27] neg_lo:[0,0,1] neg_hi:[0,0,1]
	v_pk_mul_f32 v[30:31], v[30:31], v[76:77]
	v_pk_mul_f32 v[18:19], v[18:19], v[22:23]
	v_pk_fma_f32 v[30:31], v[42:43], v[72:73], v[30:31]
	v_pk_mul_f32 v[42:43], v[28:29], v[48:49]
	v_pk_mul_f32 v[28:29], v[32:33], v[70:71] op_sel_hi:[1,0]
	v_pk_fma_f32 v[14:15], v[40:41], v[14:15], v[18:19]
	v_pk_mul_f32 v[18:19], v[20:21], v[70:71] op_sel_hi:[1,0]
	v_pk_mul_f32 v[32:33], v[28:29], v[46:47]
	v_pk_mul_f32 v[28:29], v[42:43], v[78:79]
	v_pk_mul_f32 v[18:19], v[18:19], v[34:35]
	v_pk_mul_f32 v[20:21], v[12:13], v[24:25]
	v_pk_fma_f32 v[28:29], v[32:33], v[74:75], v[28:29] neg_lo:[0,0,1] neg_hi:[0,0,1]
	v_pk_mul_f32 v[32:33], v[32:33], v[78:79]
	v_pk_fma_f32 v[20:21], v[18:19], v[16:17], v[20:21] neg_lo:[0,0,1] neg_hi:[0,0,1]
	v_pk_mul_f32 v[18:19], v[18:19], v[24:25]
	v_pk_fma_f32 v[32:33], v[42:43], v[74:75], v[32:33]
	v_pk_fma_f32 v[12:13], v[12:13], v[16:17], v[18:19]
	v_cvt_pk_bf16_f32 v82, v30, v31
	v_cvt_pk_bf16_f32 v83, v32, v33
	v_cvt_pk_bf16_f32 v84, v14, v15
	v_cvt_pk_bf16_f32 v85, v12, v13
	v_cvt_pk_bf16_f32 v86, v26, v27
	v_cvt_pk_bf16_f32 v87, v28, v29
	v_cvt_pk_bf16_f32 v88, v10, v11
	v_cvt_pk_bf16_f32 v89, v20, v21
	v_mov_b32_e32 v10, v2
	v_mov_b32_e32 v11, v2
	v_mov_b32_e32 v12, v2
	v_mov_b32_e32 v13, v2
	v_mov_b32_e32 v14, v2
	v_mov_b32_e32 v15, v2
	v_mov_b32_e32 v16, v2
	v_mov_b32_e32 v17, v2
	v_mov_b32_e32 v18, v2
	v_mov_b32_e32 v19, v2
	v_mov_b32_e32 v20, v2
	v_mov_b32_e32 v21, v2
	v_mov_b32_e32 v22, v2
	v_mov_b32_e32 v23, v2
	v_mov_b32_e32 v24, v2
	v_mov_b32_e32 v25, v2
	v_mov_b32_e32 v26, v2
	v_mov_b32_e32 v27, v2
	v_mov_b32_e32 v28, v2
	v_mov_b32_e32 v29, v2
	v_mov_b32_e32 v30, v2
	v_mov_b32_e32 v31, v2
	v_mov_b32_e32 v32, v2
	v_mov_b32_e32 v33, v2
	v_mov_b32_e32 v34, v2
	v_mov_b32_e32 v35, v2
	v_mov_b32_e32 v40, v2
	v_mov_b32_e32 v41, v2
	v_mov_b32_e32 v42, v2
	v_mov_b32_e32 v43, v2
	v_mov_b32_e32 v46, v2
	v_mov_b32_e32 v47, v2
	v_mov_b32_e32 v48, v2
	v_mov_b32_e32 v49, v2
	s_waitcnt vmcnt(0)
	ds_write_b128 v201, v[230:233] offset:18432
	v_lshl_add_u64 v[114:115], v[114:115], 0, s[4:5]
	v_add_u32_e32 v246, v199, v200
	v_add_u32_e32 v127, 0x6c00, v203
	v_add_u32_e32 v129, 0x2400, v203
	v_mov_b32_e32 v118, s88
	v_mov_b32_e32 v119, s88
	v_mov_b32_e32 v120, s88
	v_mov_b32_e32 v121, s88
	v_add_u32_e32 v247, 0x2000, v246
	v_add_u32_e32 v0, 0x3000, v246
	v_add_u32_e32 v123, 0x6800, v246
	v_add_u32_e32 v125, 0x7800, v246
	s_waitcnt lgkmcnt(0)
	ds_read_b128 v[214:217], v204 offset:0
	ds_read_b128 v[218:221], v202 offset:0
	ds_read_b128 v[222:225], v204 offset:32
	ds_read_b128 v[226:229], v202 offset:32
	ds_read_b128 v[230:233], v204 offset:64
	ds_read_b128 v[234:237], v202 offset:64
	ds_read_b128 v[238:241], v204 offset:96
	ds_read_b128 v[242:245], v202 offset:96
	s_waitcnt lgkmcnt(7)
	v_mfma_f32_32x32x16_bf16 v[50:65], v[214:217], v[94:97], 0
	s_waitcnt lgkmcnt(6)
	v_mfma_f32_32x32x16_bf16 v[66:81], v[218:221], v[94:97], 0
	s_waitcnt lgkmcnt(5)
	v_mfma_f32_32x32x16_bf16 v[50:65], v[222:225], v[90:93], v[50:65]
	s_waitcnt lgkmcnt(4)
	v_mfma_f32_32x32x16_bf16 v[66:81], v[226:229], v[90:93], v[66:81]
	s_waitcnt lgkmcnt(3)
	v_mfma_f32_32x32x16_bf16 v[50:65], v[230:233], v[86:89], v[50:65]
	s_waitcnt lgkmcnt(2)
	v_mfma_f32_32x32x16_bf16 v[66:81], v[234:237], v[86:89], v[66:81]
	s_waitcnt lgkmcnt(1)
	v_mfma_f32_32x32x16_bf16 v[50:65], v[238:241], v[82:85], v[50:65]
	s_waitcnt lgkmcnt(0)
	v_mfma_f32_32x32x16_bf16 v[66:81], v[242:245], v[82:85], v[66:81]
	s_barrier
	s_nop 15
	v_exp_f32_e32 v50, v50
	v_exp_f32_e32 v51, v51
	v_exp_f32_e32 v52, v52
	v_exp_f32_e32 v53, v53
	v_exp_f32_e32 v54, v54
	v_exp_f32_e32 v55, v55
	v_exp_f32_e32 v56, v56
	v_exp_f32_e32 v57, v57
	v_cvt_pk_bf16_f32 v50, v50, v51
	v_cvt_pk_bf16_f32 v51, v52, v53
	v_cvt_pk_bf16_f32 v52, v54, v55
	v_cvt_pk_bf16_f32 v53, v56, v57
	v_readfirstlane_b32 s4, v114
	v_readfirstlane_b32 s5, v115
	v_readfirstlane_b32 s38, v116
	v_readfirstlane_b32 s39, v117
	s_nop 4
	v_subrev_u32_e32 v114, s4, v114
	v_subrev_u32_e32 v116, s38, v116
	s_nop 1
	s_nop 0
	s_nop 0
	s_nop 0
	s_nop 0
; #define LAS __attribute__((address_space(3)))
; template <bool TRACK> ...
;     ...
;                 s0 = __builtin_amdgcn_mfma_f32_32x32x16_bf16(kf[2 * d], qf[d], s0, 0, 0, 0);
;                 s1 = __builtin_amdgcn_mfma_f32_32x32x16_bf16(kf[2 * d + 1], qf[d], s1, 0, 0, 0);
;             }
;     ...
;             for (int r = 0; r < 16; ++r) { s0[r] = __builtin_amdgcn_exp2f(s0[r]); s1[r] = __builtin_amdgcn_exp2f(s1[r]); }
;             }
;             bf16x8 pk[4];
;             { u32x4 w;
;               w.x = pk2(s0[0], s0[1]); w.y = pk2(s0[2], s0[3]); w.z = pk2(s0[4], s0[5]); w.w = pk2(s0[6], s0[7]); pk[0] = __builtin_bit_cast(bf16x8, w);
;               w.x = pk2(s0[8], s0[9]); w.y = pk2(s0[10], s0[11]); w.z = pk2(s0[12], s0[13]); w.w = pk2(s0[14], s0[15]); pk[1] = __builtin_bit_cast(bf16x8, w);
;               w.x = pk2(s1[0], s1[1]); w.y = pk2(s1[2], s1[3]); w.z = pk2(s1[4], s1[5]); w.w = pk2(s1[6], s1[7]); pk[2] = __builtin_bit_cast(bf16x8, w);
;               w.x = pk2(s1[8], s1[9]); w.y = pk2(s1[10], s1[11]); w.z = pk2(s1[12], s1[13]); w.w = pk2(s1[14], s1[15]); pk[3] = __builtin_bit_cast(bf16x8, w); }
; #pragma unroll
;             for (int kc = 0; kc < 4; ++kc) {
;                 u32x2 a, bq, c2, d2;
;                 if (!TRACK && kc < 2) { a = vq[4 * kc]; bq = vq[4 * kc + 1]; c2 = vq[4 * kc + 2]; d2 = vq[4 * kc + 3]; }
;                 else { const LAS unsigned char* vp0 = Vbuf + (r32 * 68 + kc * 16 + 4 * hi) * 2; const LAS unsigned char* vp1 = vp0 + 32 * 68 * 2;
;                     a = *(const LAS u32x2*)vp0; bq = *(const LAS u32x2*)(vp0 + 16); c2 = *(const LAS u32x2*)vp1; d2 = *(const LAS u32x2*)(vp1 + 16); }
;                 const bf16x8 v0 = __builtin_bit_cast(bf16x8, ((u32x4){a.x, a.y, bq.x, bq.y})), v1 = __builtin_bit_cast(bf16x8, ((u32x4){c2.x, c2.y, d2.x, d2.y}));
;                 o0 = __builtin_amdgcn_mfma_f32_32x32x16_bf16(v0, pk[kc], o0, 0, 0, 0);
;                 o1 = __builtin_amdgcn_mfma_f32_32x32x16_bf16(v1, pk[kc], o1, 0, 0, 0);
;                 if (!TRACK) lacc = __builtin_amdgcn_mfma_f32_32x32x16_bf16(ones, pk[kc], lacc, 0, 0, 0);
;             }
;         }
;         if (j + 1 < nt) { LAS unsigned char* nb = lds + (cur ^ 1) * 18432; *(LAS u32x4*)(nb + (srow * 72 + sc * 8) * 2) = kreg; LAS u32x2* vw_ = (LAS u32x2*)(nb + 9216 + (srow * 68 + sc * 8) * 2); vw_[0] = (u32x2){vreg.x, vreg.y}; vw_[1] = (u32x2){vreg.z, vreg.w}; }
.LBB0_167:
	global_load_dwordx4 v[98:101], v114, s[4:5]
	global_load_dwordx4 v[102:105], v116, s[38:39]
	ds_read_b128 v[106:109], v204 offset:18432
	ds_read_b128 v[110:113], v202 offset:18432
	ds_read_b128 v[158:161], v204 offset:18464
	ds_read2_b64 v[206:209], v247 offset0:128 offset1:130
	ds_read2_b64 v[210:213], v0 offset0:160 offset1:162
	s_add_u32 s4, s4, 0x2000
	s_addc_u32 s5, s5, 0
	s_add_u32 s38, s38, 0x80
	s_addc_u32 s39, s39, 0
	s_waitcnt lgkmcnt(4)
	v_mfma_f32_32x32x16_bf16 v[214:229], v[106:109], v[94:97], 0
	ds_read_b128 v[106:109], v202 offset:18464
	s_waitcnt lgkmcnt(4)
	v_mfma_f32_32x32x16_bf16 v[230:245], v[110:113], v[94:97], 0
	ds_read_b128 v[110:113], v204 offset:18496
	s_waitcnt lgkmcnt(4)
	v_mfma_f32_32x32x16_bf16 v[214:229], v[158:161], v[90:93], v[214:229]
	ds_read_b128 v[158:161], v202 offset:18496
	v_exp_f32_e32 v58, v58
	v_exp_f32_e32 v59, v59
	v_exp_f32_e32 v60, v60
	s_waitcnt lgkmcnt(2)
	v_mfma_f32_32x32x16_bf16 v[230:245], v[106:109], v[90:93], v[230:245]
	ds_read_b128 v[106:109], v204 offset:18528
	v_exp_f32_e32 v61, v61
	v_exp_f32_e32 v62, v62
	v_exp_f32_e32 v63, v63
	s_waitcnt lgkmcnt(2)
	v_mfma_f32_32x32x16_bf16 v[214:229], v[110:113], v[86:89], v[214:229]
	ds_read_b128 v[110:113], v202 offset:18528
	v_exp_f32_e32 v64, v64
	v_exp_f32_e32 v65, v65
	v_cvt_pk_bf16_f32 v54, v58, v59
	s_waitcnt lgkmcnt(2)
	v_mfma_f32_32x32x16_bf16 v[230:245], v[158:161], v[86:89], v[230:245]
	v_cvt_pk_bf16_f32 v55, v60, v61
	v_cvt_pk_bf16_f32 v56, v62, v63
	v_cvt_pk_bf16_f32 v57, v64, v65
	s_waitcnt lgkmcnt(1)
	v_mfma_f32_32x32x16_bf16 v[214:229], v[106:109], v[82:85], v[214:229]
	v_exp_f32_e32 v66, v66
	v_exp_f32_e32 v67, v67
	v_exp_f32_e32 v68, v68
	s_waitcnt lgkmcnt(0)
	v_mfma_f32_32x32x16_bf16 v[230:245], v[110:113], v[82:85], v[230:245]
	v_exp_f32_e32 v69, v69
	v_exp_f32_e32 v70, v70
	v_exp_f32_e32 v71, v71
	v_mfma_f32_32x32x16_bf16 v[2:17], v[206:209], v[50:53], v[2:17]
	ds_read2_b64 v[206:209], v247 offset0:132 offset1:134
	v_exp_f32_e32 v72, v72
	v_exp_f32_e32 v73, v73
	v_cvt_pk_bf16_f32 v66, v66, v67
	v_mfma_f32_32x32x16_bf16 v[18:33], v[210:213], v[50:53], v[18:33]
	ds_read2_b64 v[210:213], v0 offset0:164 offset1:166
	v_cvt_pk_bf16_f32 v67, v68, v69
	v_cvt_pk_bf16_f32 v68, v70, v71
	v_cvt_pk_bf16_f32 v69, v72, v73
	v_mfma_f32_4x4x4_16b_bf16 v[34:37], v[118:119], v[50:51], v[34:37]
	v_mfma_f32_4x4x4_16b_bf16 v[38:41], v[118:119], v[52:53], v[38:41]
	v_exp_f32_e32 v74, v74
	v_exp_f32_e32 v75, v75
	s_waitcnt lgkmcnt(1)
	v_mfma_f32_32x32x16_bf16 v[2:17], v[206:209], v[54:57], v[2:17]
	ds_read2_b64 v[206:209], v247 offset0:136 offset1:138
	v_exp_f32_e32 v76, v76
	v_exp_f32_e32 v77, v77
	v_exp_f32_e32 v78, v78
	s_waitcnt lgkmcnt(1)
	v_mfma_f32_32x32x16_bf16 v[18:33], v[210:213], v[54:57], v[18:33]
	ds_read2_b64 v[210:213], v0 offset0:168 offset1:170
	v_exp_f32_e32 v79, v79
	v_exp_f32_e32 v80, v80
	v_exp_f32_e32 v81, v81
	v_mfma_f32_4x4x4_16b_bf16 v[34:37], v[118:119], v[54:55], v[34:37]
	v_mfma_f32_4x4x4_16b_bf16 v[38:41], v[118:119], v[56:57], v[38:41]
	v_cvt_pk_bf16_f32 v70, v74, v75
	s_waitcnt vmcnt(1)
	ds_write_b128 v201, v[98:101] offset:0
	s_waitcnt vmcnt(0)
	ds_write2_b64 v127, v[102:103], v[104:105] offset1:1
	s_waitcnt lgkmcnt(3)
	v_mfma_f32_32x32x16_bf16 v[2:17], v[206:209], v[66:69], v[2:17]
	ds_read2_b64 v[206:209], v247 offset0:140 offset1:142
	v_cvt_pk_bf16_f32 v71, v76, v77
	v_cvt_pk_bf16_f32 v72, v78, v79
	v_cvt_pk_bf16_f32 v73, v80, v81
	s_waitcnt lgkmcnt(3)
	v_mfma_f32_32x32x16_bf16 v[18:33], v[210:213], v[66:69], v[18:33]
	ds_read2_b64 v[210:213], v0 offset0:172 offset1:174
	v_exp_f32_e32 v214, v214
	v_exp_f32_e32 v215, v215
	v_exp_f32_e32 v216, v216
	v_mfma_f32_4x4x4_16b_bf16 v[34:37], v[118:119], v[66:67], v[34:37]
	v_mfma_f32_4x4x4_16b_bf16 v[38:41], v[118:119], v[68:69], v[38:41]
	v_exp_f32_e32 v217, v217
	s_waitcnt lgkmcnt(1)
	v_mfma_f32_32x32x16_bf16 v[2:17], v[206:209], v[70:73], v[2:17]
	v_exp_f32_e32 v218, v218
	v_exp_f32_e32 v219, v219
	v_exp_f32_e32 v220, v220
	s_waitcnt lgkmcnt(0)
	v_mfma_f32_32x32x16_bf16 v[18:33], v[210:213], v[70:73], v[18:33]
	v_exp_f32_e32 v221, v221
	v_cvt_pk_bf16_f32 v214, v214, v215
	v_cvt_pk_bf16_f32 v215, v216, v217
	v_mfma_f32_4x4x4_16b_bf16 v[34:37], v[118:119], v[70:71], v[34:37]
	v_mfma_f32_4x4x4_16b_bf16 v[38:41], v[118:119], v[72:73], v[38:41]
	v_cvt_pk_bf16_f32 v216, v218, v219
	v_cvt_pk_bf16_f32 v217, v220, v221
	s_waitcnt lgkmcnt(0)
	s_barrier
; template <bool TRACK> ...
;     ...
;                 s0 = __builtin_amdgcn_mfma_f32_32x32x16_bf16(kf[2 * d], qf[d], s0, 0, 0, 0);
;                 s1 = __builtin_amdgcn_mfma_f32_32x32x16_bf16(kf[2 * d + 1], qf[d], s1, 0, 0, 0);
;             }
;     ...
;             for (int r = 0; r < 16; ++r) { s0[r] = __builtin_amdgcn_exp2f(s0[r]); s1[r] = __builtin_amdgcn_exp2f(s1[r]); }
;             }
;             bf16x8 pk[4];
;             { u32x4 w;
;               w.x = pk2(s0[0], s0[1]); w.y = pk2(s0[2], s0[3]); w.z = pk2(s0[4], s0[5]); w.w = pk2(s0[6], s0[7]); pk[0] = __builtin_bit_cast(bf16x8, w);
;               w.x = pk2(s0[8], s0[9]); w.y = pk2(s0[10], s0[11]); w.z = pk2(s0[12], s0[13]); w.w = pk2(s0[14], s0[15]); pk[1] = __builtin_bit_cast(bf16x8, w);
;               w.x = pk2(s1[0], s1[1]); w.y = pk2(s1[2], s1[3]); w.z = pk2(s1[4], s1[5]); w.w = pk2(s1[6], s1[7]); pk[2] = __builtin_bit_cast(bf16x8, w);
;               w.x = pk2(s1[8], s1[9]); w.y = pk2(s1[10], s1[11]); w.z = pk2(s1[12], s1[13]); w.w = pk2(s1[14], s1[15]); pk[3] = __builtin_bit_cast(bf16x8, w); }
; #pragma unroll
;             for (int kc = 0; kc < 4; ++kc) {
;                 u32x2 a, bq, c2, d2;
;                 if (!TRACK && kc < 2) { a = vq[4 * kc]; bq = vq[4 * kc + 1]; c2 = vq[4 * kc + 2]; d2 = vq[4 * kc + 3]; }
;                 else { const LAS unsigned char* vp0 = Vbuf + (r32 * 68 + kc * 16 + 4 * hi) * 2; const LAS unsigned char* vp1 = vp0 + 32 * 68 * 2;
;                     a = *(const LAS u32x2*)vp0; bq = *(const LAS u32x2*)(vp0 + 16); c2 = *(const LAS u32x2*)vp1; d2 = *(const LAS u32x2*)(vp1 + 16); }
;                 const bf16x8 v0 = __builtin_bit_cast(bf16x8, ((u32x4){a.x, a.y, bq.x, bq.y})), v1 = __builtin_bit_cast(bf16x8, ((u32x4){c2.x, c2.y, d2.x, d2.y}));
;                 o0 = __builtin_amdgcn_mfma_f32_32x32x16_bf16(v0, pk[kc], o0, 0, 0, 0);
;                 o1 = __builtin_amdgcn_mfma_f32_32x32x16_bf16(v1, pk[kc], o1, 0, 0, 0);
;                 if (!TRACK) lacc = __builtin_amdgcn_mfma_f32_32x32x16_bf16(ones, pk[kc], lacc, 0, 0, 0);
;             }
;         }
;         if (j + 1 < nt) { LAS unsigned char* nb = lds + (cur ^ 1) * 18432; *(LAS u32x4*)(nb + (srow * 72 + sc * 8) * 2) = kreg; LAS u32x2* vw_ = (LAS u32x2*)(nb + 9216 + (srow * 68 + sc * 8) * 2); vw_[0] = (u32x2){vreg.x, vreg.y}; vw_[1] = (u32x2){vreg.z, vreg.w}; }
;         __syncthreads();
;     }
	global_load_dwordx4 v[98:101], v114, s[4:5]
	global_load_dwordx4 v[102:105], v116, s[38:39]
	ds_read_b128 v[106:109], v204 offset:0
	ds_read_b128 v[110:113], v202 offset:0
	ds_read_b128 v[158:161], v204 offset:32
	ds_read2_b64 v[206:209], v123 offset0:128 offset1:130
	ds_read2_b64 v[210:213], v125 offset0:160 offset1:162
	s_add_u32 s4, s4, 0x2000
	s_addc_u32 s5, s5, 0
	s_add_u32 s38, s38, 0x80
	s_addc_u32 s39, s39, 0
	s_waitcnt lgkmcnt(4)
	v_mfma_f32_32x32x16_bf16 v[50:65], v[106:109], v[94:97], 0
	ds_read_b128 v[106:109], v202 offset:32
	s_waitcnt lgkmcnt(4)
	v_mfma_f32_32x32x16_bf16 v[66:81], v[110:113], v[94:97], 0
	ds_read_b128 v[110:113], v204 offset:64
	s_waitcnt lgkmcnt(4)
	v_mfma_f32_32x32x16_bf16 v[50:65], v[158:161], v[90:93], v[50:65]
	ds_read_b128 v[158:161], v202 offset:64
	v_exp_f32_e32 v222, v222
	v_exp_f32_e32 v223, v223
	v_exp_f32_e32 v224, v224
	s_waitcnt lgkmcnt(2)
	v_mfma_f32_32x32x16_bf16 v[66:81], v[106:109], v[90:93], v[66:81]
	ds_read_b128 v[106:109], v204 offset:96
	v_exp_f32_e32 v225, v225
	v_exp_f32_e32 v226, v226
	v_exp_f32_e32 v227, v227
	s_waitcnt lgkmcnt(2)
	v_mfma_f32_32x32x16_bf16 v[50:65], v[110:113], v[86:89], v[50:65]
	ds_read_b128 v[110:113], v202 offset:96
	v_exp_f32_e32 v228, v228
	v_exp_f32_e32 v229, v229
	v_cvt_pk_bf16_f32 v218, v222, v223
	s_waitcnt lgkmcnt(2)
	v_mfma_f32_32x32x16_bf16 v[66:81], v[158:161], v[86:89], v[66:81]
	v_cvt_pk_bf16_f32 v219, v224, v225
	v_cvt_pk_bf16_f32 v220, v226, v227
	v_cvt_pk_bf16_f32 v221, v228, v229
	s_waitcnt lgkmcnt(1)
	v_mfma_f32_32x32x16_bf16 v[50:65], v[106:109], v[82:85], v[50:65]
	v_exp_f32_e32 v230, v230
	v_exp_f32_e32 v231, v231
	v_exp_f32_e32 v232, v232
	s_waitcnt lgkmcnt(0)
	v_mfma_f32_32x32x16_bf16 v[66:81], v[110:113], v[82:85], v[66:81]
	v_exp_f32_e32 v233, v233
	v_exp_f32_e32 v234, v234
	v_exp_f32_e32 v235, v235
	v_mfma_f32_32x32x16_bf16 v[2:17], v[206:209], v[214:217], v[2:17]
	ds_read2_b64 v[206:209], v123 offset0:132 offset1:134
	v_exp_f32_e32 v236, v236
	v_exp_f32_e32 v237, v237
	v_cvt_pk_bf16_f32 v230, v230, v231
	v_mfma_f32_32x32x16_bf16 v[18:33], v[210:213], v[214:217], v[18:33]
	ds_read2_b64 v[210:213], v125 offset0:164 offset1:166
	v_cvt_pk_bf16_f32 v231, v232, v233
	v_cvt_pk_bf16_f32 v232, v234, v235
	v_cvt_pk_bf16_f32 v233, v236, v237
	v_mfma_f32_4x4x4_16b_bf16 v[34:37], v[118:119], v[214:215], v[34:37]
	v_mfma_f32_4x4x4_16b_bf16 v[38:41], v[118:119], v[216:217], v[38:41]
	v_exp_f32_e32 v238, v238
	v_exp_f32_e32 v239, v239
	s_waitcnt lgkmcnt(1)
	v_mfma_f32_32x32x16_bf16 v[2:17], v[206:209], v[218:221], v[2:17]
	ds_read2_b64 v[206:209], v123 offset0:136 offset1:138
	v_exp_f32_e32 v240, v240
	v_exp_f32_e32 v241, v241
	v_exp_f32_e32 v242, v242
	s_waitcnt lgkmcnt(1)
	v_mfma_f32_32x32x16_bf16 v[18:33], v[210:213], v[218:221], v[18:33]
	ds_read2_b64 v[210:213], v125 offset0:168 offset1:170
	v_exp_f32_e32 v243, v243
	v_exp_f32_e32 v244, v244
	v_exp_f32_e32 v245, v245
	v_mfma_f32_4x4x4_16b_bf16 v[34:37], v[118:119], v[218:219], v[34:37]
	v_mfma_f32_4x4x4_16b_bf16 v[38:41], v[118:119], v[220:221], v[38:41]
	v_cvt_pk_bf16_f32 v234, v238, v239
	s_waitcnt vmcnt(1)
	ds_write_b128 v201, v[98:101] offset:18432
	s_waitcnt vmcnt(0)
	ds_write2_b64 v129, v[102:103], v[104:105] offset1:1
	s_waitcnt lgkmcnt(3)
	v_mfma_f32_32x32x16_bf16 v[2:17], v[206:209], v[230:233], v[2:17]
	ds_read2_b64 v[206:209], v123 offset0:140 offset1:142
	v_cvt_pk_bf16_f32 v235, v240, v241
	v_cvt_pk_bf16_f32 v236, v242, v243
	v_cvt_pk_bf16_f32 v237, v244, v245
	s_waitcnt lgkmcnt(3)
	v_mfma_f32_32x32x16_bf16 v[18:33], v[210:213], v[230:233], v[18:33]
	ds_read2_b64 v[210:213], v125 offset0:172 offset1:174
	v_exp_f32_e32 v50, v50
	v_exp_f32_e32 v51, v51
	v_exp_f32_e32 v52, v52
	v_mfma_f32_4x4x4_16b_bf16 v[34:37], v[118:119], v[230:231], v[34:37]
	v_mfma_f32_4x4x4_16b_bf16 v[38:41], v[118:119], v[232:233], v[38:41]
	v_exp_f32_e32 v53, v53
	s_waitcnt lgkmcnt(1)
	v_mfma_f32_32x32x16_bf16 v[2:17], v[206:209], v[234:237], v[2:17]
	v_exp_f32_e32 v54, v54
	v_exp_f32_e32 v55, v55
	v_exp_f32_e32 v56, v56
	s_waitcnt lgkmcnt(0)
	v_mfma_f32_32x32x16_bf16 v[18:33], v[210:213], v[234:237], v[18:33]
	v_exp_f32_e32 v57, v57
	v_cvt_pk_bf16_f32 v50, v50, v51
	v_cvt_pk_bf16_f32 v51, v52, v53
	v_mfma_f32_4x4x4_16b_bf16 v[34:37], v[118:119], v[234:235], v[34:37]
	v_mfma_f32_4x4x4_16b_bf16 v[38:41], v[118:119], v[236:237], v[38:41]
	v_cvt_pk_bf16_f32 v52, v54, v55
	v_cvt_pk_bf16_f32 v53, v56, v57
	s_add_i32 s20, s20, 2
	s_cmp_lg_u32 s20, 36
	s_waitcnt lgkmcnt(0)
	s_barrier
	s_cbranch_scc1 .LBB0_167
	s_nop 0
	s_nop 0
	s_nop 0
	s_nop 0
	s_nop 0
	s_nop 0
	s_nop 0
	s_nop 0
	s_nop 0
	s_nop 0
	s_nop 0
	s_nop 0
	s_nop 0
	s_nop 0
	s_nop 0
	s_nop 0
	s_nop 0
	s_nop 0
	s_nop 0
	s_nop 0
	s_nop 0
	s_nop 0
	s_nop 0
	s_nop 0
	s_nop 0
	s_nop 0
	s_nop 0
	s_nop 0
	global_load_dwordx4 v[214:217], v[154:155], off offset:1280
	global_load_dwordx4 v[218:221], v[150:151], off offset:1280
	global_load_dwordx4 v[222:225], v[142:143], off offset:1280
	global_load_dwordx4 v[226:229], v[138:139], off offset:1280
	s_mov_b64 s[4:5], 0x2000
	s_mov_b64 s[38:39], 0x80
	s_nop 15
	v_readlane_b32 s89, v248, 3
	v_add_f32_e32 v34, v34, v38
	s_nop 0
	ds_bpermute_b32 v35, v188, v34
	s_waitcnt lgkmcnt(0)
	v_add_f32_e32 v34, v34, v35
	s_nop 0
	v_div_scale_f32 v0, s[20:21], v34, v34, 1.0
	v_rcp_f32_e32 v35, v0
	s_waitcnt lgkmcnt(0)
	s_barrier
; #define LAS __attribute__((address_space(3)))
; __device__ __forceinline__ unsigned pk2(float lo, float hi) { f32x2_t v = {lo, hi}; bf16x2_t b = __builtin_convertvector(v, bf16x2_t); return __builtin_bit_cast(unsigned, b); }
; __device__ __forceinline__ float silu_f(float v) { return v * __builtin_amdgcn_rcpf(1.0f + __expf(-v)); }
; template <bool TRACK> ...
;     ...
;     const float ltot = TRACK ? lsum + __shfl_xor(lsum, 32) : lacc[0]; const float inv = 1.0f / ltot;
;     {
;         LAS unsigned char* scr = lds + 40960 + wave * 8704;
; #pragma unroll
;         for (int dh = 0; dh < 2; ++dh)
; #pragma unroll
;             for (int rg = 0; rg < 4; ++rg) { const int d = dh * 32 + 8 * rg + 4 * hi;
;                 f32x4 ov; ov.x = (dh == 0 ? o0[4 * rg] : o1[4 * rg]) * inv; ov.y = (dh == 0 ? o0[4 * rg + 1] : o1[4 * rg + 1]) * inv; ov.z = (dh == 0 ? o0[4 * rg + 2] : o1[4 * rg + 2]) * inv; ov.w = (dh == 0 ? o0[4 * rg + 3] : o1[4 * rg + 3]) * inv;
;                 *(LAS f32x4*)(scr + r32 * 272 + d * 4) = ov; }
;         const int pc = lane & 7;
; #pragma unroll
;         for (int i = 0; i < 4; ++i) { const int rw = i * 8 + (lane >> 3), row = wave * 32 + rw;
;             const f32x4 oa = *(const LAS f32x4*)(scr + rw * 272 + pc * 32), ob = *(const LAS f32x4*)(scr + rw * 272 + pc * 32 + 16);
;             float gv[8]; unpack8(*(const u32x4*)(gate + (size_t)row * INW + 8 * pc), gv);
;             u32x4 w; w.x = pk2(oa.x * silu_f(gv[0]), oa.y * silu_f(gv[1])); w.y = pk2(oa.z * silu_f(gv[2]), oa.w * silu_f(gv[3]));
;             w.z = pk2(ob.x * silu_f(gv[4]), ob.y * silu_f(gv[5])); w.w = pk2(ob.z * silu_f(gv[6]), ob.w * silu_f(gv[7]));
;             *(u32x4*)(outp + (size_t)row * DM + 8 * pc) = w; }
	v_fma_f32 v36, -v0, v35, 1.0
	v_fmac_f32_e32 v35, v36, v35
	v_div_scale_f32 v36, vcc, 1.0, v34, 1.0
	v_mul_f32_e32 v37, v36, v35
	v_fma_f32 v38, -v0, v37, v36
	v_fmac_f32_e32 v37, v38, v35
	v_fma_f32 v0, -v0, v37, v36
	v_div_fmas_f32 v0, v0, v35, v37
	v_div_fixup_f32 v0, v0, v34, 1.0
	s_nop 1
	v_mul_f32_e64 v2, v2, v0
	v_mul_f32_e64 v3, v3, v0
	v_pk_mul_f32 v[4:5], v[4:5], v[0:1] op_sel_hi:[1,0]
	v_add_u32_e32 v34, v198, v156
	ds_write_b128 v34, v[2:5] offset:40960
	v_pk_mul_f32 v[2:3], v[6:7], v[0:1] op_sel_hi:[1,0]
	v_pk_mul_f32 v[4:5], v[8:9], v[0:1] op_sel_hi:[1,0]
	ds_write_b128 v34, v[2:5] offset:40992
	v_pk_mul_f32 v[2:3], v[10:11], v[0:1] op_sel_hi:[1,0]
	v_pk_mul_f32 v[4:5], v[12:13], v[0:1] op_sel_hi:[1,0]
	ds_write_b128 v34, v[2:5] offset:41024
	v_pk_mul_f32 v[2:3], v[14:15], v[0:1] op_sel_hi:[1,0]
	v_pk_mul_f32 v[4:5], v[16:17], v[0:1] op_sel_hi:[1,0]
	ds_write_b128 v34, v[2:5] offset:41056
	v_pk_mul_f32 v[2:3], v[18:19], v[0:1] op_sel_hi:[1,0]
	v_pk_mul_f32 v[4:5], v[20:21], v[0:1] op_sel_hi:[1,0]
	ds_write_b128 v34, v[2:5] offset:41088
	v_pk_mul_f32 v[2:3], v[22:23], v[0:1] op_sel_hi:[1,0]
	v_pk_mul_f32 v[4:5], v[24:25], v[0:1] op_sel_hi:[1,0]
	ds_write_b128 v34, v[2:5] offset:41120
	v_pk_mul_f32 v[2:3], v[26:27], v[0:1] op_sel_hi:[1,0]
	v_pk_mul_f32 v[4:5], v[28:29], v[0:1] op_sel_hi:[1,0]
	ds_write_b128 v34, v[2:5] offset:41152
	v_pk_mul_f32 v[2:3], v[30:31], v[0:1] op_sel_hi:[1,0]
	v_pk_mul_f32 v[4:5], v[32:33], v[0:1] op_sel_hi:[1,0]
	ds_write_b128 v34, v[2:5] offset:41184
	v_add_u32_e32 v0, v192, v193
	ds_read_b128 v[6:9], v0 offset:40960
	ds_read_b128 v[2:5], v0 offset:40976
	s_waitcnt vmcnt(3)
	v_lshlrev_b32_e32 v14, 16, v214
	v_and_b32_e32 v15, 0xffff0000, v214
	v_mul_f32_e32 v214, 0xbfb8aa3b, v14
	v_exp_f32_e32 v214, v214
	s_nop 0
	v_add_f32_e32 v214, 1.0, v214
	v_rcp_f32_e32 v16, v214
	v_mul_f32_e32 v214, 0xbfb8aa3b, v15
	v_exp_f32_e32 v214, v214
	s_nop 0
	v_add_f32_e32 v214, 1.0, v214
	v_rcp_f32_e32 v17, v214
	v_lshlrev_b32_e32 v214, 16, v215
	v_and_b32_e32 v215, 0xffff0000, v215
	v_pk_mul_f32 v[14:15], v[16:17], v[14:15]
	s_waitcnt lgkmcnt(1)
	v_pk_mul_f32 v[6:7], v[6:7], v[14:15]
	s_nop 0
	v_cvt_pk_bf16_f32 v6, v6, v7
	v_mul_f32_e32 v7, 0xbfb8aa3b, v214
	v_exp_f32_e32 v7, v7
	s_nop 0
	v_add_f32_e32 v7, 1.0, v7
	v_rcp_f32_e32 v14, v7
	v_mul_f32_e32 v7, 0xbfb8aa3b, v215
	v_exp_f32_e32 v7, v7
	s_nop 0
	v_add_f32_e32 v7, 1.0, v7
	v_rcp_f32_e32 v15, v7
	s_nop 0
	v_pk_mul_f32 v[214:215], v[14:15], v[214:215]
	s_nop 0
	v_pk_mul_f32 v[8:9], v[8:9], v[214:215]
	s_nop 0
	v_cvt_pk_bf16_f32 v7, v8, v9
	v_lshlrev_b32_e32 v8, 16, v216
	v_and_b32_e32 v9, 0xffff0000, v216
	v_mul_f32_e32 v214, 0xbfb8aa3b, v8
	v_mul_f32_e32 v215, 0xbfb8aa3b, v9
	v_exp_f32_e32 v214, v214
	v_exp_f32_e32 v215, v215
	v_add_f32_e32 v214, 1.0, v214
	v_add_f32_e32 v215, 1.0, v215
	v_rcp_f32_e32 v214, v214
	v_rcp_f32_e32 v215, v215
	s_nop 0
	v_pk_mul_f32 v[8:9], v[214:215], v[8:9]
	s_waitcnt lgkmcnt(0)
	v_pk_mul_f32 v[2:3], v[2:3], v[8:9]
	s_nop 0
	v_cvt_pk_bf16_f32 v8, v2, v3
	v_lshlrev_b32_e32 v2, 16, v217
	v_mul_f32_e32 v9, 0xbfb8aa3b, v2
	v_exp_f32_e32 v9, v9
	v_and_b32_e32 v3, 0xffff0000, v217
	v_add_f32_e32 v9, 1.0, v9
	v_rcp_f32_e32 v214, v9
	v_mul_f32_e32 v9, 0xbfb8aa3b, v3
	v_exp_f32_e32 v9, v9
	s_nop 0
	v_add_f32_e32 v9, 1.0, v9
	v_rcp_f32_e32 v215, v9
	s_nop 0
	v_pk_mul_f32 v[2:3], v[214:215], v[2:3]
	s_nop 0
	v_pk_mul_f32 v[2:3], v[4:5], v[2:3]
	s_nop 0
	v_cvt_pk_bf16_f32 v9, v2, v3
	global_store_dwordx4 v[152:153], v[6:9], off
	ds_read_b128 v[6:9], v0 offset:43136
	ds_read_b128 v[2:5], v0 offset:43152
	s_waitcnt vmcnt(3)
	v_lshlrev_b32_e32 v14, 16, v218
	v_and_b32_e32 v15, 0xffff0000, v218
	v_mul_f32_e32 v218, 0xbfb8aa3b, v14
	v_exp_f32_e32 v218, v218
	s_nop 0
	v_add_f32_e32 v218, 1.0, v218
	v_rcp_f32_e32 v16, v218
	v_mul_f32_e32 v218, 0xbfb8aa3b, v15
	v_exp_f32_e32 v218, v218
	s_nop 0
	v_add_f32_e32 v218, 1.0, v218
	v_rcp_f32_e32 v17, v218
	v_lshlrev_b32_e32 v218, 16, v219
	v_and_b32_e32 v219, 0xffff0000, v219
	v_pk_mul_f32 v[14:15], v[16:17], v[14:15]
	s_waitcnt lgkmcnt(1)
	v_pk_mul_f32 v[6:7], v[6:7], v[14:15]
	s_nop 0
	v_cvt_pk_bf16_f32 v6, v6, v7
	v_mul_f32_e32 v7, 0xbfb8aa3b, v218
	v_exp_f32_e32 v7, v7
	s_nop 0
	v_add_f32_e32 v7, 1.0, v7
	v_rcp_f32_e32 v14, v7
	v_mul_f32_e32 v7, 0xbfb8aa3b, v219
	v_exp_f32_e32 v7, v7
	s_nop 0
	v_add_f32_e32 v7, 1.0, v7
	v_rcp_f32_e32 v15, v7
	s_nop 0
	v_pk_mul_f32 v[218:219], v[14:15], v[218:219]
	s_nop 0
	v_pk_mul_f32 v[8:9], v[8:9], v[218:219]
	s_nop 0
	v_cvt_pk_bf16_f32 v7, v8, v9
	v_lshlrev_b32_e32 v8, 16, v220
	v_and_b32_e32 v9, 0xffff0000, v220
	v_mul_f32_e32 v218, 0xbfb8aa3b, v8
	v_mul_f32_e32 v219, 0xbfb8aa3b, v9
	v_exp_f32_e32 v218, v218
	v_exp_f32_e32 v219, v219
	v_add_f32_e32 v218, 1.0, v218
	v_add_f32_e32 v219, 1.0, v219
	v_rcp_f32_e32 v218, v218
	v_rcp_f32_e32 v219, v219
	s_nop 0
	v_pk_mul_f32 v[8:9], v[218:219], v[8:9]
	s_waitcnt lgkmcnt(0)
; #define LAS __attribute__((address_space(3)))
; __device__ __forceinline__ unsigned pk2(float lo, float hi) { f32x2_t v = {lo, hi}; bf16x2_t b = __builtin_convertvector(v, bf16x2_t); return __builtin_bit_cast(unsigned, b); }
; __device__ __forceinline__ float silu_f(float v) { return v * __builtin_amdgcn_rcpf(1.0f + __expf(-v)); }
; template <bool TRACK> ...
;     ...
;         for (int i = 0; i < 4; ++i) { const int rw = i * 8 + (lane >> 3), row = wave * 32 + rw;
;             const f32x4 oa = *(const LAS f32x4*)(scr + rw * 272 + pc * 32), ob = *(const LAS f32x4*)(scr + rw * 272 + pc * 32 + 16);
;             float gv[8]; unpack8(*(const u32x4*)(gate + (size_t)row * INW + 8 * pc), gv);
;             u32x4 w; w.x = pk2(oa.x * silu_f(gv[0]), oa.y * silu_f(gv[1])); w.y = pk2(oa.z * silu_f(gv[2]), oa.w * silu_f(gv[3]));
;             w.z = pk2(ob.x * silu_f(gv[4]), ob.y * silu_f(gv[5])); w.w = pk2(ob.z * silu_f(gv[6]), ob.w * silu_f(gv[7]));
;             *(u32x4*)(outp + (size_t)row * DM + 8 * pc) = w; }
	v_pk_mul_f32 v[2:3], v[2:3], v[8:9]
	s_nop 0
	v_cvt_pk_bf16_f32 v8, v2, v3
	v_lshlrev_b32_e32 v2, 16, v221
	v_mul_f32_e32 v9, 0xbfb8aa3b, v2
	v_exp_f32_e32 v9, v9
	v_and_b32_e32 v3, 0xffff0000, v221
	v_add_f32_e32 v9, 1.0, v9
	v_rcp_f32_e32 v218, v9
	v_mul_f32_e32 v9, 0xbfb8aa3b, v3
	v_exp_f32_e32 v9, v9
	s_nop 0
	v_add_f32_e32 v9, 1.0, v9
	v_rcp_f32_e32 v219, v9
	s_nop 0
	v_pk_mul_f32 v[2:3], v[218:219], v[2:3]
	s_nop 0
	v_pk_mul_f32 v[2:3], v[4:5], v[2:3]
	s_nop 0
	v_cvt_pk_bf16_f32 v9, v2, v3
	global_store_dwordx4 v[144:145], v[6:9], off
	ds_read_b128 v[6:9], v0 offset:45312
	ds_read_b128 v[2:5], v0 offset:45328
	s_waitcnt vmcnt(3)
	v_lshlrev_b32_e32 v14, 16, v222
	v_and_b32_e32 v15, 0xffff0000, v222
	v_mul_f32_e32 v222, 0xbfb8aa3b, v14
	v_exp_f32_e32 v222, v222
	s_nop 0
	v_add_f32_e32 v222, 1.0, v222
	v_rcp_f32_e32 v16, v222
	v_mul_f32_e32 v222, 0xbfb8aa3b, v15
	v_exp_f32_e32 v222, v222
	s_nop 0
	v_add_f32_e32 v222, 1.0, v222
	v_rcp_f32_e32 v17, v222
	v_lshlrev_b32_e32 v222, 16, v223
	v_and_b32_e32 v223, 0xffff0000, v223
	v_pk_mul_f32 v[14:15], v[16:17], v[14:15]
	s_waitcnt lgkmcnt(1)
	v_pk_mul_f32 v[6:7], v[6:7], v[14:15]
	s_nop 0
	v_cvt_pk_bf16_f32 v6, v6, v7
	v_mul_f32_e32 v7, 0xbfb8aa3b, v222
	v_exp_f32_e32 v7, v7
	s_nop 0
	v_add_f32_e32 v7, 1.0, v7
	v_rcp_f32_e32 v14, v7
	v_mul_f32_e32 v7, 0xbfb8aa3b, v223
	v_exp_f32_e32 v7, v7
	s_nop 0
	v_add_f32_e32 v7, 1.0, v7
	v_rcp_f32_e32 v15, v7
	s_nop 0
	v_pk_mul_f32 v[222:223], v[14:15], v[222:223]
	s_nop 0
	v_pk_mul_f32 v[8:9], v[8:9], v[222:223]
	s_nop 0
	v_cvt_pk_bf16_f32 v7, v8, v9
	v_lshlrev_b32_e32 v8, 16, v224
	v_and_b32_e32 v9, 0xffff0000, v224
	v_mul_f32_e32 v222, 0xbfb8aa3b, v8
	v_mul_f32_e32 v223, 0xbfb8aa3b, v9
	v_exp_f32_e32 v222, v222
	v_exp_f32_e32 v223, v223
	v_add_f32_e32 v222, 1.0, v222
	v_add_f32_e32 v223, 1.0, v223
	v_rcp_f32_e32 v222, v222
	v_rcp_f32_e32 v223, v223
	s_nop 0
	v_pk_mul_f32 v[8:9], v[222:223], v[8:9]
	s_waitcnt lgkmcnt(0)
	v_pk_mul_f32 v[2:3], v[2:3], v[8:9]
	s_nop 0
	v_cvt_pk_bf16_f32 v8, v2, v3
	v_lshlrev_b32_e32 v2, 16, v225
	v_mul_f32_e32 v9, 0xbfb8aa3b, v2
	v_exp_f32_e32 v9, v9
	v_and_b32_e32 v3, 0xffff0000, v225
	v_add_f32_e32 v9, 1.0, v9
	v_rcp_f32_e32 v222, v9
	v_mul_f32_e32 v9, 0xbfb8aa3b, v3
	v_exp_f32_e32 v9, v9
	s_nop 0
	v_add_f32_e32 v9, 1.0, v9
	v_rcp_f32_e32 v223, v9
	s_nop 0
	v_pk_mul_f32 v[2:3], v[222:223], v[2:3]
	s_nop 0
	v_pk_mul_f32 v[2:3], v[4:5], v[2:3]
	s_nop 0
	v_cvt_pk_bf16_f32 v9, v2, v3
	global_store_dwordx4 v[140:141], v[6:9], off
	ds_read_b128 v[6:9], v0 offset:47488
	ds_read_b128 v[2:5], v0 offset:47504
	s_waitcnt vmcnt(3)
	v_lshlrev_b32_e32 v14, 16, v226
	v_mul_f32_e32 v0, 0xbfb8aa3b, v14
	v_exp_f32_e32 v0, v0
	v_and_b32_e32 v15, 0xffff0000, v226
	v_lshlrev_b32_e32 v226, 16, v227
	v_and_b32_e32 v227, 0xffff0000, v227
	v_add_f32_e32 v0, 1.0, v0
	v_rcp_f32_e32 v16, v0
	v_mul_f32_e32 v0, 0xbfb8aa3b, v15
	v_exp_f32_e32 v0, v0
	s_nop 0
	v_add_f32_e32 v0, 1.0, v0
	v_rcp_f32_e32 v17, v0
	v_mul_f32_e32 v0, 0xbfb8aa3b, v226
	v_exp_f32_e32 v0, v0
	v_pk_mul_f32 v[14:15], v[16:17], v[14:15]
	s_waitcnt lgkmcnt(1)
	v_pk_mul_f32 v[6:7], v[6:7], v[14:15]
	v_add_f32_e32 v0, 1.0, v0
	v_rcp_f32_e32 v14, v0
	v_mul_f32_e32 v0, 0xbfb8aa3b, v227
	v_exp_f32_e32 v0, v0
	v_cvt_pk_bf16_f32 v6, v6, v7
	v_add_f32_e32 v0, 1.0, v0
	v_rcp_f32_e32 v15, v0
	s_nop 0
	v_pk_mul_f32 v[226:227], v[14:15], v[226:227]
	s_nop 0
	v_pk_mul_f32 v[8:9], v[8:9], v[226:227]
	s_nop 0
	v_cvt_pk_bf16_f32 v7, v8, v9
	v_lshlrev_b32_e32 v8, 16, v228
	v_mul_f32_e32 v0, 0xbfb8aa3b, v8
	v_exp_f32_e32 v0, v0
	v_and_b32_e32 v9, 0xffff0000, v228
	v_add_f32_e32 v0, 1.0, v0
	v_rcp_f32_e32 v226, v0
	v_mul_f32_e32 v0, 0xbfb8aa3b, v9
	v_exp_f32_e32 v0, v0
	s_nop 0
	v_add_f32_e32 v0, 1.0, v0
	v_rcp_f32_e32 v227, v0
	s_nop 0
	v_pk_mul_f32 v[8:9], v[226:227], v[8:9]
	s_waitcnt lgkmcnt(0)
	v_pk_mul_f32 v[2:3], v[2:3], v[8:9]
	s_nop 0
	v_cvt_pk_bf16_f32 v8, v2, v3
	v_lshlrev_b32_e32 v2, 16, v229
	v_mul_f32_e32 v0, 0xbfb8aa3b, v2
	v_exp_f32_e32 v0, v0
	v_and_b32_e32 v3, 0xffff0000, v229
	v_add_f32_e32 v0, 1.0, v0
	v_rcp_f32_e32 v226, v0
	v_mul_f32_e32 v0, 0xbfb8aa3b, v3
	v_exp_f32_e32 v0, v0
	s_nop 0
	v_add_f32_e32 v0, 1.0, v0
	v_rcp_f32_e32 v227, v0
	s_nop 0
	v_pk_mul_f32 v[2:3], v[226:227], v[2:3]
	s_nop 0
	v_pk_mul_f32 v[2:3], v[4:5], v[2:3]
	s_nop 0
	v_cvt_pk_bf16_f32 v9, v2, v3
	global_store_dwordx4 v[136:137], v[6:9], off
